# phase 5 tile queue prologue: the first two tile indices claimed with back-to-back atomics and broadcast together (one round trip and one barrier fewer per block)
# baseline (speedup 1.0000x reference)
.Lser_exit:
	s_nop 0
	s_nop 0
	s_nop 0
	s_nop 0
	s_nop 0
	s_nop 0
	s_nop 0
	s_nop 0
	s_nop 0
	s_nop 0
	v_lshlrev_b32_e32 v157, 2, v0

.Ltq_c1:
	s_mov_b64 exec, s[26:27]
	s_and_saveexec_b64 s[26:27], s[4:5]
	s_cbranch_execz .Ltq_c2
	global_atomic_add v252, v37, v251, s[10:11] sc0
.Ltq_c2:
	s_mov_b64 exec, s[26:27]
	s_waitcnt vmcnt(0)
	s_and_saveexec_b64 s[26:27], s[4:5]
	ds_write_b32 v32, v250
	ds_write_b32 v32, v252 offset:4
	s_mov_b64 exec, s[26:27]
	s_waitcnt lgkmcnt(0)
	s_barrier
	ds_read2_b32 v[34:35], v32 offset1:1
	s_waitcnt lgkmcnt(0)
	v_readfirstlane_b32 s6, v34
	v_readfirstlane_b32 s77, v35
	s_nop 3
	s_cmp_ge_u32 s6, 0x780
	s_cbranch_scc1 .LBB0_571
	s_cmp_lt_u32 s6, 0x580
	s_cbranch_scc0 .Ltq_oth_p0
	s_mul_i32 s7, s6, 0x1746
	s_lshr_b32 s7, s7, 20
	s_mul_i32 s8, s7, 0xb0
	s_sub_u32 s8, s6, s8
	s_mul_i32 s9, s7, 0xb00000
	s_lshl_b32 s29, s8, 8
	s_add_u32 s9, s9, s29
	s_add_u32 s12, s52, s9
	s_addc_u32 s13, s53, 0
	s_mov_b32 s14, 0xb000
	s_mov_b32 s15, 0x160000
	s_lshl_b32 s9, s8, 18
	s_lshl_b32 s29, s7, 9
	s_add_u32 s9, s9, s29
	s_add_u32 s9, s9, 0x3a00000
	s_add_u32 s16, s70, s9
	s_addc_u32 s17, s71, 0
	s_mov_b32 s18, 12
	s_lshl_b32 s9, s7, 10
	s_add_u32 s20, s50, s9
	s_addc_u32 s21, s51, 0
	s_mov_b32 s25, 1
	s_branch .Ltq_ld_p0

.Ltq_sd_p0:
	global_load_dwordx4 v[40:43], v180, s[12:13]
	global_load_dwordx4 v[44:47], v181, s[12:13]
	global_load_dwordx4 v[48:51], v182, s[12:13]
	global_load_dwordx4 v[52:55], v183, s[12:13]
	global_load_dwordx4 v[56:59], v184, s[12:13]
	global_load_dwordx4 v[60:63], v185, s[12:13]
	global_load_dwordx4 v[64:67], v186, s[12:13]
	global_load_dwordx4 v[68:71], v187, s[12:13]
	s_mov_b32 s6, s77
	s_mov_b32 s74, 0
	s_mov_b32 s76, 0
	s_cmp_ge_u32 s6, 0x780
	s_cbranch_scc1 .Ltq_pw
	s_and_saveexec_b64 s[26:27], s[4:5]
	s_cbranch_execz .Ltq_c3
	global_atomic_add v250, v37, v251, s[10:11] sc0

.Ltq_sd_p1:
	global_load_dwordx4 v[140:143], v180, s[12:13]
	global_load_dwordx4 v[144:147], v181, s[12:13]
	global_load_dwordx4 v[148:151], v182, s[12:13]
	global_load_dwordx4 v[152:155], v183, s[12:13]
	global_load_dwordx4 v[156:159], v184, s[12:13]
	global_load_dwordx4 v[160:163], v185, s[12:13]
	global_load_dwordx4 v[164:167], v186, s[12:13]
	global_load_dwordx4 v[168:171], v187, s[12:13]
	s_mov_b32 s74, 1
	s_mov_b32 s76, 1
	s_waitcnt vmcnt(8)
	s_branch .Ltq_st0
.Ltq_pw:
	s_waitcnt vmcnt(0)
.Ltq_st0:
	s_mov_b32 s75, 0
	s_cmp_eq_u32 s76, 0
	s_cbranch_scc1 .Ltq_pr0
	s_and_saveexec_b64 s[26:27], s[4:5]
	ds_write_b32 v32, v250
	s_mov_b64 exec, s[26:27]
	s_waitcnt lgkmcnt(0)
	s_barrier
	ds_read_b32 v33, v32
	s_waitcnt lgkmcnt(0)
	v_readfirstlane_b32 s6, v33
	s_nop 3
	s_cmp_ge_u32 s6, 0x780
	s_cselect_b32 s76, 0, 1
	s_cbranch_scc1 .Ltq_pr0
	s_and_saveexec_b64 s[26:27], s[4:5]
	s_cbranch_execz .Ltq_c4
	global_atomic_add v250, v37, v251, s[10:11] sc0
